# NSA selected branch: forced blocks evaluated once before the gathered items (hand-written full pass, packed math) - replaces the max-only pass before and the full pass after; O/l/m kept in spare regis
# speedup vs baseline: 1.0160x; 1.0072x over previous
.LBB0_1389:
	s_waitcnt lgkmcnt(0)
	s_add_u32 s4, s16, s42
	s_addc_u32 s5, s17, s43
	s_add_u32 s48, s4, 0x3a00000
	s_addc_u32 s49, s5, 0
	s_waitcnt lgkmcnt(0)
	s_cmp_lt_i32 s44, 2
	s_cselect_b64 s[18:19], -1, 0
	s_add_u32 s50, s4, 0x4200000
	s_addc_u32 s51, s5, 0
	v_mov_b32_e32 v2, 0
	v_mov_b32_e32 v3, 0
	v_mov_b32_e32 v4, 0
	v_mov_b32_e32 v5, 0
	v_mov_b32_e32 v6, 0
	v_mov_b32_e32 v7, 0
	v_mov_b32_e32 v8, 0
	v_mov_b32_e32 v9, 0
	v_mov_b32_e32 v10, 0
	v_mov_b32_e32 v11, 0
	v_mov_b32_e32 v12, 0
	v_mov_b32_e32 v13, 0
	v_mov_b32_e32 v14, 0
	v_mov_b32_e32 v15, 0
	v_mov_b32_e32 v16, 0
	v_mov_b32_e32 v17, 0
	v_mov_b32_e32 v18, 0
	v_mov_b32_e32 v19, 0
	v_mov_b32_e32 v20, 0
	v_mov_b32_e32 v21, 0
	v_mov_b32_e32 v22, 0
	v_mov_b32_e32 v23, 0
	v_mov_b32_e32 v24, 0
	v_mov_b32_e32 v25, 0
	v_mov_b32_e32 v26, 0
	v_mov_b32_e32 v27, 0
	v_mov_b32_e32 v28, 0
	v_mov_b32_e32 v29, 0
	v_mov_b32_e32 v30, 0
	v_mov_b32_e32 v31, 0
	v_mov_b32_e32 v32, 0
	v_mov_b32_e32 v33, 0
	v_mov_b32_e32 v1, 0
	v_mov_b32_e32 v162, 0xff800000
	v_mov_b32_e32 v236, 0x3fb8aa3b
	ds_read_b128 v[82:85], v224
	ds_read_b128 v[86:89], v224 offset:32
	ds_read_b128 v[90:93], v224 offset:64
	ds_read_b128 v[94:97], v224 offset:96
	s_lshl_b32 s4, s44, 13
	s_add_u32 s12, s48, s4
	s_addc_u32 s13, s49, 0
	s_waitcnt vmcnt(0)
	global_load_dwordx4 v[98:101], v194, s[12:13]
	global_load_dwordx4 v[102:105], v194, s[12:13] offset:1024
	global_load_dwordx4 v[106:109], v194, s[12:13] offset:2048
	global_load_dwordx4 v[110:113], v194, s[12:13] offset:3072
	global_load_dwordx4 v[114:117], v200, s[12:13]
	global_load_dwordx4 v[118:121], v202, s[12:13]
	global_load_dwordx4 v[122:125], v204, s[12:13]
	global_load_dwordx4 v[126:129], v206, s[12:13]
	s_waitcnt lgkmcnt(0)
	s_mov_b32 s26, s44
	s_lshl_b32 s4, s26, 13
	s_add_u32 s12, s50, s4
	s_addc_u32 s13, s51, 0
	global_load_dwordx4 v[130:133], v194, s[12:13]
	global_load_dwordx4 v[146:149], v200, s[12:13]
	global_load_dwordx4 v[134:137], v194, s[12:13] offset:1024
	global_load_dwordx4 v[150:153], v202, s[12:13]
	global_load_dwordx4 v[138:141], v194, s[12:13] offset:2048
	global_load_dwordx4 v[154:157], v204, s[12:13]
	global_load_dwordx4 v[142:145], v194, s[12:13] offset:3072
	global_load_dwordx4 v[158:161], v206, s[12:13]
	s_lshl_b32 s4, s26, 6
	v_subrev_u32_e32 v163, s4, v223
	v_sub_u32_e32 v163, v163, v226
	v_lshl_add_u32 v163, v163, 2, v225
	ds_read2_b32 v[66:67], v163 offset0:64 offset1:63
	ds_read2_b32 v[68:69], v163 offset0:62 offset1:61
	ds_read2_b32 v[70:71], v163 offset0:56 offset1:55
	ds_read2_b32 v[72:73], v163 offset0:54 offset1:53
	ds_read2_b32 v[74:75], v163 offset0:48 offset1:47
	ds_read2_b32 v[76:77], v163 offset0:46 offset1:45
	ds_read2_b32 v[78:79], v163 offset0:40 offset1:39
	ds_read2_b32 v[80:81], v163 offset0:38 offset1:37
	s_waitcnt vmcnt(8)
	v_mfma_f32_32x32x16_bf16 v[34:49], v[98:101], v[82:85], 0
	v_mfma_f32_32x32x16_bf16 v[50:65], v[114:117], v[82:85], 0
	v_mfma_f32_32x32x16_bf16 v[34:49], v[102:105], v[86:89], v[34:49]
	v_mfma_f32_32x32x16_bf16 v[50:65], v[118:121], v[86:89], v[50:65]
	v_mfma_f32_32x32x16_bf16 v[34:49], v[106:109], v[90:93], v[34:49]
	v_mfma_f32_32x32x16_bf16 v[50:65], v[122:125], v[90:93], v[50:65]
	v_mfma_f32_32x32x16_bf16 v[34:49], v[110:113], v[94:97], v[34:49]
	v_mfma_f32_32x32x16_bf16 v[50:65], v[126:129], v[94:97], v[50:65]
	s_cmp_gt_i32 s44, 0
	s_cbranch_scc1 .Lfe_a_has
	s_nop 9
	s_branch .Lfe_a_nok
.Lfe_a_has:
	s_add_i32 s4, s44, -1
	s_lshl_b32 s4, s4, 13
	s_add_u32 s12, s48, s4
	s_addc_u32 s13, s49, 0
	global_load_dwordx4 v[98:101], v194, s[12:13]
	global_load_dwordx4 v[102:105], v194, s[12:13] offset:1024
	global_load_dwordx4 v[106:109], v194, s[12:13] offset:2048
	global_load_dwordx4 v[110:113], v194, s[12:13] offset:3072
	global_load_dwordx4 v[114:117], v200, s[12:13]
	global_load_dwordx4 v[118:121], v202, s[12:13]
	global_load_dwordx4 v[122:125], v204, s[12:13]
	global_load_dwordx4 v[126:129], v206, s[12:13]
.Lfe_a_nok:
	s_waitcnt lgkmcnt(0)
	v_pk_fma_f32 v[34:35], v[34:35], v[236:237], v[66:67] op_sel_hi:[1,0,1]
	v_pk_fma_f32 v[36:37], v[36:37], v[236:237], v[68:69] op_sel_hi:[1,0,1]
	v_pk_fma_f32 v[38:39], v[38:39], v[236:237], v[70:71] op_sel_hi:[1,0,1]
	v_pk_fma_f32 v[40:41], v[40:41], v[236:237], v[72:73] op_sel_hi:[1,0,1]
	v_pk_fma_f32 v[42:43], v[42:43], v[236:237], v[74:75] op_sel_hi:[1,0,1]
	v_pk_fma_f32 v[44:45], v[44:45], v[236:237], v[76:77] op_sel_hi:[1,0,1]
	v_pk_fma_f32 v[46:47], v[46:47], v[236:237], v[78:79] op_sel_hi:[1,0,1]
	v_pk_fma_f32 v[48:49], v[48:49], v[236:237], v[80:81] op_sel_hi:[1,0,1]
	ds_read2_b32 v[66:67], v163 offset0:32 offset1:31
	ds_read2_b32 v[68:69], v163 offset0:30 offset1:29
	ds_read2_b32 v[70:71], v163 offset0:24 offset1:23
	ds_read2_b32 v[72:73], v163 offset0:22 offset1:21
	ds_read2_b32 v[74:75], v163 offset0:16 offset1:15
	ds_read2_b32 v[76:77], v163 offset0:14 offset1:13
	ds_read2_b32 v[78:79], v163 offset0:8 offset1:7
	ds_read2_b32 v[80:81], v163 offset0:6 offset1:5
	s_waitcnt lgkmcnt(0)
	v_pk_fma_f32 v[50:51], v[50:51], v[236:237], v[66:67] op_sel_hi:[1,0,1]
	v_pk_fma_f32 v[52:53], v[52:53], v[236:237], v[68:69] op_sel_hi:[1,0,1]
	v_pk_fma_f32 v[54:55], v[54:55], v[236:237], v[70:71] op_sel_hi:[1,0,1]
	v_pk_fma_f32 v[56:57], v[56:57], v[236:237], v[72:73] op_sel_hi:[1,0,1]
	v_pk_fma_f32 v[58:59], v[58:59], v[236:237], v[74:75] op_sel_hi:[1,0,1]
	v_pk_fma_f32 v[60:61], v[60:61], v[236:237], v[76:77] op_sel_hi:[1,0,1]
	v_pk_fma_f32 v[62:63], v[62:63], v[236:237], v[78:79] op_sel_hi:[1,0,1]
	v_pk_fma_f32 v[64:65], v[64:65], v[236:237], v[80:81] op_sel_hi:[1,0,1]
	v_max3_f32 v172, v34, v35, v36
	v_max3_f32 v172, v172, v37, v38
	v_max3_f32 v172, v172, v39, v40
	v_max3_f32 v172, v172, v41, v42
	v_max3_f32 v172, v172, v43, v44
	v_max3_f32 v172, v172, v45, v46
	v_max3_f32 v172, v172, v47, v48
	v_max3_f32 v172, v172, v49, v49
	v_max3_f32 v177, v50, v51, v52
	v_max3_f32 v177, v177, v53, v54
	v_max3_f32 v177, v177, v55, v56
	v_max3_f32 v177, v177, v57, v58
	v_max3_f32 v177, v177, v59, v60
	v_max3_f32 v177, v177, v61, v62
	v_max3_f32 v177, v177, v63, v64
	v_max3_f32 v177, v177, v65, v65
	v_max_f32_e32 v172, v172, v177
	v_mov_b32_e32 v173, v172
	s_nop 1
	v_permlane32_swap_b32_e32 v172, v173
	v_max3_f32 v177, v162, v172, v173
	v_cmp_neq_f32_e32 vcc, s68, v177
	s_nop 1
	v_cndmask_b32_e32 v174, 0, v177, vcc
	v_cmp_neq_f32_e32 vcc, v177, v162
	s_cbranch_vccz .Lfe_nr_a
	v_sub_f32_e32 v176, v162, v174
	v_exp_f32_e32 v176, v176
	s_nop 0
	v_pk_mul_f32 v[2:3], v[2:3], v[176:177] op_sel_hi:[1,0]
	v_pk_mul_f32 v[4:5], v[4:5], v[176:177] op_sel_hi:[1,0]
	v_pk_mul_f32 v[6:7], v[6:7], v[176:177] op_sel_hi:[1,0]
	v_pk_mul_f32 v[8:9], v[8:9], v[176:177] op_sel_hi:[1,0]
	v_pk_mul_f32 v[10:11], v[10:11], v[176:177] op_sel_hi:[1,0]
	v_pk_mul_f32 v[12:13], v[12:13], v[176:177] op_sel_hi:[1,0]
	v_pk_mul_f32 v[14:15], v[14:15], v[176:177] op_sel_hi:[1,0]
	v_pk_mul_f32 v[16:17], v[16:17], v[176:177] op_sel_hi:[1,0]
	v_pk_mul_f32 v[18:19], v[18:19], v[176:177] op_sel_hi:[1,0]
	v_pk_mul_f32 v[20:21], v[20:21], v[176:177] op_sel_hi:[1,0]
	v_pk_mul_f32 v[22:23], v[22:23], v[176:177] op_sel_hi:[1,0]
	v_pk_mul_f32 v[24:25], v[24:25], v[176:177] op_sel_hi:[1,0]
	v_pk_mul_f32 v[26:27], v[26:27], v[176:177] op_sel_hi:[1,0]
	v_pk_mul_f32 v[28:29], v[28:29], v[176:177] op_sel_hi:[1,0]
	v_pk_mul_f32 v[30:31], v[30:31], v[176:177] op_sel_hi:[1,0]
	v_pk_mul_f32 v[32:33], v[32:33], v[176:177] op_sel_hi:[1,0]
	v_mul_f32_e32 v1, v176, v1
.Lfe_nr_a:
	v_mov_b32_e32 v162, v177
	v_pk_add_f32 v[34:35], v[34:35], v[174:175] op_sel_hi:[1,0] neg_lo:[0,1] neg_hi:[0,1]
	v_pk_add_f32 v[36:37], v[36:37], v[174:175] op_sel_hi:[1,0] neg_lo:[0,1] neg_hi:[0,1]
	v_pk_add_f32 v[38:39], v[38:39], v[174:175] op_sel_hi:[1,0] neg_lo:[0,1] neg_hi:[0,1]
	v_pk_add_f32 v[40:41], v[40:41], v[174:175] op_sel_hi:[1,0] neg_lo:[0,1] neg_hi:[0,1]
	v_exp_f32_e32 v34, v34
	v_exp_f32_e32 v35, v35
	v_exp_f32_e32 v36, v36
	v_exp_f32_e32 v37, v37
	v_exp_f32_e32 v38, v38
	v_exp_f32_e32 v39, v39
	v_exp_f32_e32 v40, v40
	v_exp_f32_e32 v41, v41
	v_pk_add_f32 v[238:239], v[34:35], v[36:37]
	v_pk_add_f32 v[238:239], v[238:239], v[38:39]
	v_pk_add_f32 v[238:239], v[238:239], v[40:41]
	v_cvt_pk_bf16_f32 v164, v34, v35
	v_cvt_pk_bf16_f32 v165, v36, v37
	v_cvt_pk_bf16_f32 v166, v38, v39
	v_cvt_pk_bf16_f32 v167, v40, v41
	v_pk_add_f32 v[42:43], v[42:43], v[174:175] op_sel_hi:[1,0] neg_lo:[0,1] neg_hi:[0,1]
	v_pk_add_f32 v[44:45], v[44:45], v[174:175] op_sel_hi:[1,0] neg_lo:[0,1] neg_hi:[0,1]
	v_pk_add_f32 v[46:47], v[46:47], v[174:175] op_sel_hi:[1,0] neg_lo:[0,1] neg_hi:[0,1]
	v_pk_add_f32 v[48:49], v[48:49], v[174:175] op_sel_hi:[1,0] neg_lo:[0,1] neg_hi:[0,1]
	s_cmp_gt_i32 s44, 0
	s_cbranch_scc1 .Lfe_a_w8
	s_waitcnt vmcnt(0)
	s_branch .Lfe_a_pv

.Lfe_a_pv:
	v_mfma_f32_32x32x16_bf16 v[2:17], v[130:133], v[164:167], v[2:17]
	v_mfma_f32_32x32x16_bf16 v[18:33], v[146:149], v[164:167], v[18:33]
	v_exp_f32_e32 v42, v42
	v_exp_f32_e32 v43, v43
	v_exp_f32_e32 v44, v44
	v_exp_f32_e32 v45, v45
	v_exp_f32_e32 v46, v46
	v_exp_f32_e32 v47, v47
	v_exp_f32_e32 v48, v48
	v_exp_f32_e32 v49, v49
	v_pk_add_f32 v[238:239], v[238:239], v[42:43]
	v_pk_add_f32 v[238:239], v[238:239], v[44:45]
	v_pk_add_f32 v[238:239], v[238:239], v[46:47]
	v_pk_add_f32 v[238:239], v[238:239], v[48:49]
	v_cvt_pk_bf16_f32 v168, v42, v43
	v_cvt_pk_bf16_f32 v169, v44, v45
	v_cvt_pk_bf16_f32 v170, v46, v47
	v_cvt_pk_bf16_f32 v171, v48, v49
	v_pk_add_f32 v[50:51], v[50:51], v[174:175] op_sel_hi:[1,0] neg_lo:[0,1] neg_hi:[0,1]
	v_pk_add_f32 v[52:53], v[52:53], v[174:175] op_sel_hi:[1,0] neg_lo:[0,1] neg_hi:[0,1]
	v_pk_add_f32 v[54:55], v[54:55], v[174:175] op_sel_hi:[1,0] neg_lo:[0,1] neg_hi:[0,1]
	v_pk_add_f32 v[56:57], v[56:57], v[174:175] op_sel_hi:[1,0] neg_lo:[0,1] neg_hi:[0,1]
	v_mfma_f32_32x32x16_bf16 v[2:17], v[134:137], v[168:171], v[2:17]
	v_mfma_f32_32x32x16_bf16 v[18:33], v[150:153], v[168:171], v[18:33]
	v_exp_f32_e32 v50, v50
	v_exp_f32_e32 v51, v51
	v_exp_f32_e32 v52, v52
	v_exp_f32_e32 v53, v53
	v_exp_f32_e32 v54, v54
	v_exp_f32_e32 v55, v55
	v_exp_f32_e32 v56, v56
	v_exp_f32_e32 v57, v57
	v_pk_add_f32 v[238:239], v[238:239], v[50:51]
	v_pk_add_f32 v[238:239], v[238:239], v[52:53]
	v_pk_add_f32 v[238:239], v[238:239], v[54:55]
	v_pk_add_f32 v[238:239], v[238:239], v[56:57]
	v_cvt_pk_bf16_f32 v164, v50, v51
	v_cvt_pk_bf16_f32 v165, v52, v53
	v_cvt_pk_bf16_f32 v166, v54, v55
	v_cvt_pk_bf16_f32 v167, v56, v57
	v_pk_add_f32 v[58:59], v[58:59], v[174:175] op_sel_hi:[1,0] neg_lo:[0,1] neg_hi:[0,1]
	v_pk_add_f32 v[60:61], v[60:61], v[174:175] op_sel_hi:[1,0] neg_lo:[0,1] neg_hi:[0,1]
	v_pk_add_f32 v[62:63], v[62:63], v[174:175] op_sel_hi:[1,0] neg_lo:[0,1] neg_hi:[0,1]
	v_pk_add_f32 v[64:65], v[64:65], v[174:175] op_sel_hi:[1,0] neg_lo:[0,1] neg_hi:[0,1]
	v_mfma_f32_32x32x16_bf16 v[2:17], v[138:141], v[164:167], v[2:17]
	v_mfma_f32_32x32x16_bf16 v[18:33], v[154:157], v[164:167], v[18:33]
	v_exp_f32_e32 v58, v58
	v_exp_f32_e32 v59, v59
	v_exp_f32_e32 v60, v60
	v_exp_f32_e32 v61, v61
	v_exp_f32_e32 v62, v62
	v_exp_f32_e32 v63, v63
	v_exp_f32_e32 v64, v64
	v_exp_f32_e32 v65, v65
	v_pk_add_f32 v[238:239], v[238:239], v[58:59]
	v_pk_add_f32 v[238:239], v[238:239], v[60:61]
	v_pk_add_f32 v[238:239], v[238:239], v[62:63]
	v_pk_add_f32 v[238:239], v[238:239], v[64:65]
	v_cvt_pk_bf16_f32 v168, v58, v59
	v_cvt_pk_bf16_f32 v169, v60, v61
	v_cvt_pk_bf16_f32 v170, v62, v63
	v_cvt_pk_bf16_f32 v171, v64, v65
	s_nop 1
	v_mfma_f32_32x32x16_bf16 v[2:17], v[142:145], v[168:171], v[2:17]
	v_mfma_f32_32x32x16_bf16 v[18:33], v[158:161], v[168:171], v[18:33]
	v_add_f32_e32 v240, v238, v239
	v_add_f32_e32 v1, v1, v240
	s_cmp_gt_i32 s44, 0
	s_cbranch_scc0 .Lfe_done
	s_add_i32 s26, s44, -1
	s_lshl_b32 s4, s26, 13
	s_add_u32 s12, s50, s4
	s_addc_u32 s13, s51, 0
	global_load_dwordx4 v[130:133], v194, s[12:13]
	global_load_dwordx4 v[146:149], v200, s[12:13]
	global_load_dwordx4 v[134:137], v194, s[12:13] offset:1024
	global_load_dwordx4 v[150:153], v202, s[12:13]
	global_load_dwordx4 v[138:141], v194, s[12:13] offset:2048
	global_load_dwordx4 v[154:157], v204, s[12:13]
	global_load_dwordx4 v[142:145], v194, s[12:13] offset:3072
	global_load_dwordx4 v[158:161], v206, s[12:13]
	s_lshl_b32 s4, s26, 6
	v_subrev_u32_e32 v163, s4, v223
	v_sub_u32_e32 v163, v163, v226
	v_lshl_add_u32 v163, v163, 2, v225
	ds_read2_b32 v[66:67], v163 offset0:64 offset1:63
	ds_read2_b32 v[68:69], v163 offset0:62 offset1:61
	ds_read2_b32 v[70:71], v163 offset0:56 offset1:55
	ds_read2_b32 v[72:73], v163 offset0:54 offset1:53
	ds_read2_b32 v[74:75], v163 offset0:48 offset1:47
	ds_read2_b32 v[76:77], v163 offset0:46 offset1:45
	ds_read2_b32 v[78:79], v163 offset0:40 offset1:39
	ds_read2_b32 v[80:81], v163 offset0:38 offset1:37
	s_waitcnt vmcnt(8)
	v_mfma_f32_32x32x16_bf16 v[34:49], v[98:101], v[82:85], 0
	v_mfma_f32_32x32x16_bf16 v[50:65], v[114:117], v[82:85], 0
	v_mfma_f32_32x32x16_bf16 v[34:49], v[102:105], v[86:89], v[34:49]
	v_mfma_f32_32x32x16_bf16 v[50:65], v[118:121], v[86:89], v[50:65]
	v_mfma_f32_32x32x16_bf16 v[34:49], v[106:109], v[90:93], v[34:49]
	v_mfma_f32_32x32x16_bf16 v[50:65], v[122:125], v[90:93], v[50:65]
	v_mfma_f32_32x32x16_bf16 v[34:49], v[110:113], v[94:97], v[34:49]
	v_mfma_f32_32x32x16_bf16 v[50:65], v[126:129], v[94:97], v[50:65]
	s_cmp_gt_i32 s44, 1
	s_cbranch_scc1 .Lfe_b_has
	s_nop 9
	s_branch .Lfe_b_nok
.Lfe_b_has:
	s_mov_b32 s4, 0
	s_lshl_b32 s4, s4, 13
	s_add_u32 s12, s48, s4
	s_addc_u32 s13, s49, 0
	global_load_dwordx4 v[98:101], v194, s[12:13]
	global_load_dwordx4 v[102:105], v194, s[12:13] offset:1024
	global_load_dwordx4 v[106:109], v194, s[12:13] offset:2048
	global_load_dwordx4 v[110:113], v194, s[12:13] offset:3072
	global_load_dwordx4 v[114:117], v200, s[12:13]
	global_load_dwordx4 v[118:121], v202, s[12:13]
	global_load_dwordx4 v[122:125], v204, s[12:13]
	global_load_dwordx4 v[126:129], v206, s[12:13]

.Lfe_nr_b:
	v_mov_b32_e32 v162, v177
	v_pk_add_f32 v[34:35], v[34:35], v[174:175] op_sel_hi:[1,0] neg_lo:[0,1] neg_hi:[0,1]
	v_pk_add_f32 v[36:37], v[36:37], v[174:175] op_sel_hi:[1,0] neg_lo:[0,1] neg_hi:[0,1]
	v_pk_add_f32 v[38:39], v[38:39], v[174:175] op_sel_hi:[1,0] neg_lo:[0,1] neg_hi:[0,1]
	v_pk_add_f32 v[40:41], v[40:41], v[174:175] op_sel_hi:[1,0] neg_lo:[0,1] neg_hi:[0,1]
	v_exp_f32_e32 v34, v34
	v_exp_f32_e32 v35, v35
	v_exp_f32_e32 v36, v36
	v_exp_f32_e32 v37, v37
	v_exp_f32_e32 v38, v38
	v_exp_f32_e32 v39, v39
	v_exp_f32_e32 v40, v40
	v_exp_f32_e32 v41, v41
	v_pk_add_f32 v[238:239], v[34:35], v[36:37]
	v_pk_add_f32 v[238:239], v[238:239], v[38:39]
	v_pk_add_f32 v[238:239], v[238:239], v[40:41]
	v_cvt_pk_bf16_f32 v164, v34, v35
	v_cvt_pk_bf16_f32 v165, v36, v37
	v_cvt_pk_bf16_f32 v166, v38, v39
	v_cvt_pk_bf16_f32 v167, v40, v41
	v_pk_add_f32 v[42:43], v[42:43], v[174:175] op_sel_hi:[1,0] neg_lo:[0,1] neg_hi:[0,1]
	v_pk_add_f32 v[44:45], v[44:45], v[174:175] op_sel_hi:[1,0] neg_lo:[0,1] neg_hi:[0,1]
	v_pk_add_f32 v[46:47], v[46:47], v[174:175] op_sel_hi:[1,0] neg_lo:[0,1] neg_hi:[0,1]
	v_pk_add_f32 v[48:49], v[48:49], v[174:175] op_sel_hi:[1,0] neg_lo:[0,1] neg_hi:[0,1]
	s_cmp_gt_i32 s44, 1
	s_cbranch_scc1 .Lfe_b_w8
	s_waitcnt vmcnt(0)
	s_branch .Lfe_b_pv

.Lfe_b_pv:
	v_mfma_f32_32x32x16_bf16 v[2:17], v[130:133], v[164:167], v[2:17]
	v_mfma_f32_32x32x16_bf16 v[18:33], v[146:149], v[164:167], v[18:33]
	v_exp_f32_e32 v42, v42
	v_exp_f32_e32 v43, v43
	v_exp_f32_e32 v44, v44
	v_exp_f32_e32 v45, v45
	v_exp_f32_e32 v46, v46
	v_exp_f32_e32 v47, v47
	v_exp_f32_e32 v48, v48
	v_exp_f32_e32 v49, v49
	v_pk_add_f32 v[238:239], v[238:239], v[42:43]
	v_pk_add_f32 v[238:239], v[238:239], v[44:45]
	v_pk_add_f32 v[238:239], v[238:239], v[46:47]
	v_pk_add_f32 v[238:239], v[238:239], v[48:49]
	v_cvt_pk_bf16_f32 v168, v42, v43
	v_cvt_pk_bf16_f32 v169, v44, v45
	v_cvt_pk_bf16_f32 v170, v46, v47
	v_cvt_pk_bf16_f32 v171, v48, v49
	v_pk_add_f32 v[50:51], v[50:51], v[174:175] op_sel_hi:[1,0] neg_lo:[0,1] neg_hi:[0,1]
	v_pk_add_f32 v[52:53], v[52:53], v[174:175] op_sel_hi:[1,0] neg_lo:[0,1] neg_hi:[0,1]
	v_pk_add_f32 v[54:55], v[54:55], v[174:175] op_sel_hi:[1,0] neg_lo:[0,1] neg_hi:[0,1]
	v_pk_add_f32 v[56:57], v[56:57], v[174:175] op_sel_hi:[1,0] neg_lo:[0,1] neg_hi:[0,1]
	v_mfma_f32_32x32x16_bf16 v[2:17], v[134:137], v[168:171], v[2:17]
	v_mfma_f32_32x32x16_bf16 v[18:33], v[150:153], v[168:171], v[18:33]
	v_exp_f32_e32 v50, v50
	v_exp_f32_e32 v51, v51
	v_exp_f32_e32 v52, v52
	v_exp_f32_e32 v53, v53
	v_exp_f32_e32 v54, v54
	v_exp_f32_e32 v55, v55
	v_exp_f32_e32 v56, v56
	v_exp_f32_e32 v57, v57
	v_pk_add_f32 v[238:239], v[238:239], v[50:51]
	v_pk_add_f32 v[238:239], v[238:239], v[52:53]
	v_pk_add_f32 v[238:239], v[238:239], v[54:55]
	v_pk_add_f32 v[238:239], v[238:239], v[56:57]
	v_cvt_pk_bf16_f32 v164, v50, v51
	v_cvt_pk_bf16_f32 v165, v52, v53
	v_cvt_pk_bf16_f32 v166, v54, v55
	v_cvt_pk_bf16_f32 v167, v56, v57
	v_pk_add_f32 v[58:59], v[58:59], v[174:175] op_sel_hi:[1,0] neg_lo:[0,1] neg_hi:[0,1]
	v_pk_add_f32 v[60:61], v[60:61], v[174:175] op_sel_hi:[1,0] neg_lo:[0,1] neg_hi:[0,1]
	v_pk_add_f32 v[62:63], v[62:63], v[174:175] op_sel_hi:[1,0] neg_lo:[0,1] neg_hi:[0,1]
	v_pk_add_f32 v[64:65], v[64:65], v[174:175] op_sel_hi:[1,0] neg_lo:[0,1] neg_hi:[0,1]
	v_mfma_f32_32x32x16_bf16 v[2:17], v[138:141], v[164:167], v[2:17]
	v_mfma_f32_32x32x16_bf16 v[18:33], v[154:157], v[164:167], v[18:33]
	v_exp_f32_e32 v58, v58
	v_exp_f32_e32 v59, v59
	v_exp_f32_e32 v60, v60
	v_exp_f32_e32 v61, v61
	v_exp_f32_e32 v62, v62
	v_exp_f32_e32 v63, v63
	v_exp_f32_e32 v64, v64
	v_exp_f32_e32 v65, v65
	v_pk_add_f32 v[238:239], v[238:239], v[58:59]
	v_pk_add_f32 v[238:239], v[238:239], v[60:61]
	v_pk_add_f32 v[238:239], v[238:239], v[62:63]
	v_pk_add_f32 v[238:239], v[238:239], v[64:65]
	v_cvt_pk_bf16_f32 v168, v58, v59
	v_cvt_pk_bf16_f32 v169, v60, v61
	v_cvt_pk_bf16_f32 v170, v62, v63
	v_cvt_pk_bf16_f32 v171, v64, v65
	s_nop 1
	v_mfma_f32_32x32x16_bf16 v[2:17], v[142:145], v[168:171], v[2:17]
	v_mfma_f32_32x32x16_bf16 v[18:33], v[158:161], v[168:171], v[18:33]
	v_add_f32_e32 v240, v238, v239
	v_add_f32_e32 v1, v1, v240
	s_cmp_gt_i32 s44, 1
	s_cbranch_scc0 .Lfe_done
	s_cmp_eq_u32 s44, 2
	s_cbranch_scc1 .Lfe_cnear
	s_mov_b32 s26, 0
	s_lshl_b32 s4, s26, 13
	s_add_u32 s12, s50, s4
	s_addc_u32 s13, s51, 0
	global_load_dwordx4 v[130:133], v194, s[12:13]
	global_load_dwordx4 v[146:149], v200, s[12:13]
	global_load_dwordx4 v[134:137], v194, s[12:13] offset:1024
	global_load_dwordx4 v[150:153], v202, s[12:13]
	global_load_dwordx4 v[138:141], v194, s[12:13] offset:2048
	global_load_dwordx4 v[154:157], v204, s[12:13]
	global_load_dwordx4 v[142:145], v194, s[12:13] offset:3072
	global_load_dwordx4 v[158:161], v206, s[12:13]
	s_waitcnt vmcnt(8)
	v_mfma_f32_32x32x16_bf16 v[34:49], v[98:101], v[82:85], 0
	v_mfma_f32_32x32x16_bf16 v[50:65], v[114:117], v[82:85], 0
	v_mfma_f32_32x32x16_bf16 v[34:49], v[102:105], v[86:89], v[34:49]
	v_mfma_f32_32x32x16_bf16 v[50:65], v[118:121], v[86:89], v[50:65]
	v_mfma_f32_32x32x16_bf16 v[34:49], v[106:109], v[90:93], v[34:49]
	v_mfma_f32_32x32x16_bf16 v[50:65], v[122:125], v[90:93], v[50:65]
	v_mfma_f32_32x32x16_bf16 v[34:49], v[110:113], v[94:97], v[34:49]
	v_mfma_f32_32x32x16_bf16 v[50:65], v[126:129], v[94:97], v[50:65]
	s_nop 7
	s_nop 3
	v_max3_f32 v172, v34, v35, v36
	v_max3_f32 v172, v172, v37, v38
	v_max3_f32 v172, v172, v39, v40
	v_max3_f32 v172, v172, v41, v42
	v_max3_f32 v172, v172, v43, v44
	v_max3_f32 v172, v172, v45, v46
	v_max3_f32 v172, v172, v47, v48
	v_max3_f32 v172, v172, v49, v49
	v_max3_f32 v177, v50, v51, v52
	v_max3_f32 v177, v177, v53, v54
	v_max3_f32 v177, v177, v55, v56
	v_max3_f32 v177, v177, v57, v58
	v_max3_f32 v177, v177, v59, v60
	v_max3_f32 v177, v177, v61, v62
	v_max3_f32 v177, v177, v63, v64
	v_max3_f32 v177, v177, v65, v65
	v_max_f32_e32 v172, v172, v177
	v_fmamk_f32 v172, v172, 0x3fb8aa3b, v208
	v_mov_b32_e32 v173, v172
	s_nop 1
	v_permlane32_swap_b32_e32 v172, v173
	v_max3_f32 v177, v162, v172, v173
	v_cmp_neq_f32_e32 vcc, s68, v177
	s_nop 1
	v_cndmask_b32_e32 v174, 0, v177, vcc
	v_cmp_neq_f32_e32 vcc, v177, v162
	s_cbranch_vccz .Lfe_nr_c
	v_sub_f32_e32 v176, v162, v174
	v_exp_f32_e32 v176, v176
	s_nop 0
	v_pk_mul_f32 v[2:3], v[2:3], v[176:177] op_sel_hi:[1,0]
	v_pk_mul_f32 v[4:5], v[4:5], v[176:177] op_sel_hi:[1,0]
	v_pk_mul_f32 v[6:7], v[6:7], v[176:177] op_sel_hi:[1,0]
	v_pk_mul_f32 v[8:9], v[8:9], v[176:177] op_sel_hi:[1,0]
	v_pk_mul_f32 v[10:11], v[10:11], v[176:177] op_sel_hi:[1,0]
	v_pk_mul_f32 v[12:13], v[12:13], v[176:177] op_sel_hi:[1,0]
	v_pk_mul_f32 v[14:15], v[14:15], v[176:177] op_sel_hi:[1,0]
	v_pk_mul_f32 v[16:17], v[16:17], v[176:177] op_sel_hi:[1,0]
	v_pk_mul_f32 v[18:19], v[18:19], v[176:177] op_sel_hi:[1,0]
	v_pk_mul_f32 v[20:21], v[20:21], v[176:177] op_sel_hi:[1,0]
	v_pk_mul_f32 v[22:23], v[22:23], v[176:177] op_sel_hi:[1,0]
	v_pk_mul_f32 v[24:25], v[24:25], v[176:177] op_sel_hi:[1,0]
	v_pk_mul_f32 v[26:27], v[26:27], v[176:177] op_sel_hi:[1,0]
	v_pk_mul_f32 v[28:29], v[28:29], v[176:177] op_sel_hi:[1,0]
	v_pk_mul_f32 v[30:31], v[30:31], v[176:177] op_sel_hi:[1,0]
	v_pk_mul_f32 v[32:33], v[32:33], v[176:177] op_sel_hi:[1,0]
	v_mul_f32_e32 v1, v176, v1
.Lfe_nr_c:
	v_mov_b32_e32 v162, v177
	v_sub_f32_e32 v234, v208, v174
	v_pk_fma_f32 v[34:35], v[34:35], v[236:237], v[234:235] op_sel_hi:[1,0,0]
	v_pk_fma_f32 v[36:37], v[36:37], v[236:237], v[234:235] op_sel_hi:[1,0,0]
	v_pk_fma_f32 v[38:39], v[38:39], v[236:237], v[234:235] op_sel_hi:[1,0,0]
	v_pk_fma_f32 v[40:41], v[40:41], v[236:237], v[234:235] op_sel_hi:[1,0,0]
	v_exp_f32_e32 v34, v34
	v_exp_f32_e32 v35, v35
	v_exp_f32_e32 v36, v36
	v_exp_f32_e32 v37, v37
	v_exp_f32_e32 v38, v38
	v_exp_f32_e32 v39, v39
	v_exp_f32_e32 v40, v40
	v_exp_f32_e32 v41, v41
	v_pk_add_f32 v[238:239], v[34:35], v[36:37]
	v_pk_add_f32 v[238:239], v[238:239], v[38:39]
	v_pk_add_f32 v[238:239], v[238:239], v[40:41]
	v_cvt_pk_bf16_f32 v164, v34, v35
	v_cvt_pk_bf16_f32 v165, v36, v37
	v_cvt_pk_bf16_f32 v166, v38, v39
	v_cvt_pk_bf16_f32 v167, v40, v41
	v_pk_fma_f32 v[42:43], v[42:43], v[236:237], v[234:235] op_sel_hi:[1,0,0]
	v_pk_fma_f32 v[44:45], v[44:45], v[236:237], v[234:235] op_sel_hi:[1,0,0]
	v_pk_fma_f32 v[46:47], v[46:47], v[236:237], v[234:235] op_sel_hi:[1,0,0]
	v_pk_fma_f32 v[48:49], v[48:49], v[236:237], v[234:235] op_sel_hi:[1,0,0]
	s_waitcnt vmcnt(0)
	v_mfma_f32_32x32x16_bf16 v[2:17], v[130:133], v[164:167], v[2:17]
	v_mfma_f32_32x32x16_bf16 v[18:33], v[146:149], v[164:167], v[18:33]
	v_exp_f32_e32 v42, v42
	v_exp_f32_e32 v43, v43
	v_exp_f32_e32 v44, v44
	v_exp_f32_e32 v45, v45
	v_exp_f32_e32 v46, v46
	v_exp_f32_e32 v47, v47
	v_exp_f32_e32 v48, v48
	v_exp_f32_e32 v49, v49
	v_pk_add_f32 v[238:239], v[238:239], v[42:43]
	v_pk_add_f32 v[238:239], v[238:239], v[44:45]
	v_pk_add_f32 v[238:239], v[238:239], v[46:47]
	v_pk_add_f32 v[238:239], v[238:239], v[48:49]
	v_cvt_pk_bf16_f32 v168, v42, v43
	v_cvt_pk_bf16_f32 v169, v44, v45
	v_cvt_pk_bf16_f32 v170, v46, v47
	v_cvt_pk_bf16_f32 v171, v48, v49
	v_pk_fma_f32 v[50:51], v[50:51], v[236:237], v[234:235] op_sel_hi:[1,0,0]
	v_pk_fma_f32 v[52:53], v[52:53], v[236:237], v[234:235] op_sel_hi:[1,0,0]
	v_pk_fma_f32 v[54:55], v[54:55], v[236:237], v[234:235] op_sel_hi:[1,0,0]
	v_pk_fma_f32 v[56:57], v[56:57], v[236:237], v[234:235] op_sel_hi:[1,0,0]
	v_mfma_f32_32x32x16_bf16 v[2:17], v[134:137], v[168:171], v[2:17]
	v_mfma_f32_32x32x16_bf16 v[18:33], v[150:153], v[168:171], v[18:33]
	v_exp_f32_e32 v50, v50
	v_exp_f32_e32 v51, v51
	v_exp_f32_e32 v52, v52
	v_exp_f32_e32 v53, v53
	v_exp_f32_e32 v54, v54
	v_exp_f32_e32 v55, v55
	v_exp_f32_e32 v56, v56
	v_exp_f32_e32 v57, v57
	v_pk_add_f32 v[238:239], v[238:239], v[50:51]
	v_pk_add_f32 v[238:239], v[238:239], v[52:53]
	v_pk_add_f32 v[238:239], v[238:239], v[54:55]
	v_pk_add_f32 v[238:239], v[238:239], v[56:57]
	v_cvt_pk_bf16_f32 v164, v50, v51
	v_cvt_pk_bf16_f32 v165, v52, v53
	v_cvt_pk_bf16_f32 v166, v54, v55
	v_cvt_pk_bf16_f32 v167, v56, v57
	v_pk_fma_f32 v[58:59], v[58:59], v[236:237], v[234:235] op_sel_hi:[1,0,0]
	v_pk_fma_f32 v[60:61], v[60:61], v[236:237], v[234:235] op_sel_hi:[1,0,0]
	v_pk_fma_f32 v[62:63], v[62:63], v[236:237], v[234:235] op_sel_hi:[1,0,0]
	v_pk_fma_f32 v[64:65], v[64:65], v[236:237], v[234:235] op_sel_hi:[1,0,0]
	v_mfma_f32_32x32x16_bf16 v[2:17], v[138:141], v[164:167], v[2:17]
	v_mfma_f32_32x32x16_bf16 v[18:33], v[154:157], v[164:167], v[18:33]
	v_exp_f32_e32 v58, v58
	v_exp_f32_e32 v59, v59
	v_exp_f32_e32 v60, v60
	v_exp_f32_e32 v61, v61
	v_exp_f32_e32 v62, v62
	v_exp_f32_e32 v63, v63
	v_exp_f32_e32 v64, v64
	v_exp_f32_e32 v65, v65
	v_pk_add_f32 v[238:239], v[238:239], v[58:59]
	v_pk_add_f32 v[238:239], v[238:239], v[60:61]
	v_pk_add_f32 v[238:239], v[238:239], v[62:63]
	v_pk_add_f32 v[238:239], v[238:239], v[64:65]
	v_cvt_pk_bf16_f32 v168, v58, v59
	v_cvt_pk_bf16_f32 v169, v60, v61
	v_cvt_pk_bf16_f32 v170, v62, v63
	v_cvt_pk_bf16_f32 v171, v64, v65
	s_nop 1
	v_mfma_f32_32x32x16_bf16 v[2:17], v[142:145], v[168:171], v[2:17]
	v_mfma_f32_32x32x16_bf16 v[18:33], v[158:161], v[168:171], v[18:33]
	v_add_f32_e32 v240, v238, v239
	v_add_f32_e32 v1, v1, v240
	s_branch .Lfe_done
.Lfe_cnear:
	s_mov_b32 s26, 0
	s_lshl_b32 s4, s26, 13
	s_add_u32 s12, s50, s4
	s_addc_u32 s13, s51, 0
	global_load_dwordx4 v[130:133], v194, s[12:13]
	global_load_dwordx4 v[146:149], v200, s[12:13]
	global_load_dwordx4 v[134:137], v194, s[12:13] offset:1024
	global_load_dwordx4 v[150:153], v202, s[12:13]
	global_load_dwordx4 v[138:141], v194, s[12:13] offset:2048
	global_load_dwordx4 v[154:157], v204, s[12:13]
	global_load_dwordx4 v[142:145], v194, s[12:13] offset:3072
	global_load_dwordx4 v[158:161], v206, s[12:13]
	s_lshl_b32 s4, s26, 6
	v_subrev_u32_e32 v163, s4, v223
	v_sub_u32_e32 v163, v163, v226
	v_lshl_add_u32 v163, v163, 2, v225
	ds_read2_b32 v[66:67], v163 offset0:64 offset1:63
	ds_read2_b32 v[68:69], v163 offset0:62 offset1:61
	ds_read2_b32 v[70:71], v163 offset0:56 offset1:55
	ds_read2_b32 v[72:73], v163 offset0:54 offset1:53
	ds_read2_b32 v[74:75], v163 offset0:48 offset1:47
	ds_read2_b32 v[76:77], v163 offset0:46 offset1:45
	ds_read2_b32 v[78:79], v163 offset0:40 offset1:39
	ds_read2_b32 v[80:81], v163 offset0:38 offset1:37
	s_waitcnt vmcnt(8)
	v_mfma_f32_32x32x16_bf16 v[34:49], v[98:101], v[82:85], 0
	v_mfma_f32_32x32x16_bf16 v[50:65], v[114:117], v[82:85], 0
	v_mfma_f32_32x32x16_bf16 v[34:49], v[102:105], v[86:89], v[34:49]
	v_mfma_f32_32x32x16_bf16 v[50:65], v[118:121], v[86:89], v[50:65]
	v_mfma_f32_32x32x16_bf16 v[34:49], v[106:109], v[90:93], v[34:49]
	v_mfma_f32_32x32x16_bf16 v[50:65], v[122:125], v[90:93], v[50:65]
	v_mfma_f32_32x32x16_bf16 v[34:49], v[110:113], v[94:97], v[34:49]
	v_mfma_f32_32x32x16_bf16 v[50:65], v[126:129], v[94:97], v[50:65]
	s_nop 7
	s_nop 3
	s_waitcnt lgkmcnt(0)
	v_pk_fma_f32 v[34:35], v[34:35], v[236:237], v[66:67] op_sel_hi:[1,0,1]
	v_pk_fma_f32 v[36:37], v[36:37], v[236:237], v[68:69] op_sel_hi:[1,0,1]
	v_pk_fma_f32 v[38:39], v[38:39], v[236:237], v[70:71] op_sel_hi:[1,0,1]
	v_pk_fma_f32 v[40:41], v[40:41], v[236:237], v[72:73] op_sel_hi:[1,0,1]
	v_pk_fma_f32 v[42:43], v[42:43], v[236:237], v[74:75] op_sel_hi:[1,0,1]
	v_pk_fma_f32 v[44:45], v[44:45], v[236:237], v[76:77] op_sel_hi:[1,0,1]
	v_pk_fma_f32 v[46:47], v[46:47], v[236:237], v[78:79] op_sel_hi:[1,0,1]
	v_pk_fma_f32 v[48:49], v[48:49], v[236:237], v[80:81] op_sel_hi:[1,0,1]
	ds_read2_b32 v[66:67], v163 offset0:32 offset1:31
	ds_read2_b32 v[68:69], v163 offset0:30 offset1:29
	ds_read2_b32 v[70:71], v163 offset0:24 offset1:23
	ds_read2_b32 v[72:73], v163 offset0:22 offset1:21
	ds_read2_b32 v[74:75], v163 offset0:16 offset1:15
	ds_read2_b32 v[76:77], v163 offset0:14 offset1:13
	ds_read2_b32 v[78:79], v163 offset0:8 offset1:7
	ds_read2_b32 v[80:81], v163 offset0:6 offset1:5
	s_waitcnt lgkmcnt(0)
	v_pk_fma_f32 v[50:51], v[50:51], v[236:237], v[66:67] op_sel_hi:[1,0,1]
	v_pk_fma_f32 v[52:53], v[52:53], v[236:237], v[68:69] op_sel_hi:[1,0,1]
	v_pk_fma_f32 v[54:55], v[54:55], v[236:237], v[70:71] op_sel_hi:[1,0,1]
	v_pk_fma_f32 v[56:57], v[56:57], v[236:237], v[72:73] op_sel_hi:[1,0,1]
	v_pk_fma_f32 v[58:59], v[58:59], v[236:237], v[74:75] op_sel_hi:[1,0,1]
	v_pk_fma_f32 v[60:61], v[60:61], v[236:237], v[76:77] op_sel_hi:[1,0,1]
	v_pk_fma_f32 v[62:63], v[62:63], v[236:237], v[78:79] op_sel_hi:[1,0,1]
	v_pk_fma_f32 v[64:65], v[64:65], v[236:237], v[80:81] op_sel_hi:[1,0,1]
	v_max3_f32 v172, v34, v35, v36
	v_max3_f32 v172, v172, v37, v38
	v_max3_f32 v172, v172, v39, v40
	v_max3_f32 v172, v172, v41, v42
	v_max3_f32 v172, v172, v43, v44
	v_max3_f32 v172, v172, v45, v46
	v_max3_f32 v172, v172, v47, v48
	v_max3_f32 v172, v172, v49, v49
	v_max3_f32 v177, v50, v51, v52
	v_max3_f32 v177, v177, v53, v54
	v_max3_f32 v177, v177, v55, v56
	v_max3_f32 v177, v177, v57, v58
	v_max3_f32 v177, v177, v59, v60
	v_max3_f32 v177, v177, v61, v62
	v_max3_f32 v177, v177, v63, v64
	v_max3_f32 v177, v177, v65, v65
	v_max_f32_e32 v172, v172, v177
	v_mov_b32_e32 v173, v172
	s_nop 1
	v_permlane32_swap_b32_e32 v172, v173
	v_max3_f32 v177, v162, v172, v173
	v_cmp_neq_f32_e32 vcc, s68, v177
	s_nop 1
	v_cndmask_b32_e32 v174, 0, v177, vcc
	v_cmp_neq_f32_e32 vcc, v177, v162
	s_cbranch_vccz .Lfe_nr_d
	v_sub_f32_e32 v176, v162, v174
	v_exp_f32_e32 v176, v176
	s_nop 0
	v_pk_mul_f32 v[2:3], v[2:3], v[176:177] op_sel_hi:[1,0]
	v_pk_mul_f32 v[4:5], v[4:5], v[176:177] op_sel_hi:[1,0]
	v_pk_mul_f32 v[6:7], v[6:7], v[176:177] op_sel_hi:[1,0]
	v_pk_mul_f32 v[8:9], v[8:9], v[176:177] op_sel_hi:[1,0]
	v_pk_mul_f32 v[10:11], v[10:11], v[176:177] op_sel_hi:[1,0]
	v_pk_mul_f32 v[12:13], v[12:13], v[176:177] op_sel_hi:[1,0]
	v_pk_mul_f32 v[14:15], v[14:15], v[176:177] op_sel_hi:[1,0]
	v_pk_mul_f32 v[16:17], v[16:17], v[176:177] op_sel_hi:[1,0]
	v_pk_mul_f32 v[18:19], v[18:19], v[176:177] op_sel_hi:[1,0]
	v_pk_mul_f32 v[20:21], v[20:21], v[176:177] op_sel_hi:[1,0]
	v_pk_mul_f32 v[22:23], v[22:23], v[176:177] op_sel_hi:[1,0]
	v_pk_mul_f32 v[24:25], v[24:25], v[176:177] op_sel_hi:[1,0]
	v_pk_mul_f32 v[26:27], v[26:27], v[176:177] op_sel_hi:[1,0]
	v_pk_mul_f32 v[28:29], v[28:29], v[176:177] op_sel_hi:[1,0]
	v_pk_mul_f32 v[30:31], v[30:31], v[176:177] op_sel_hi:[1,0]
	v_pk_mul_f32 v[32:33], v[32:33], v[176:177] op_sel_hi:[1,0]
	v_mul_f32_e32 v1, v176, v1
.Lfe_nr_d:
	v_mov_b32_e32 v162, v177
	v_pk_add_f32 v[34:35], v[34:35], v[174:175] op_sel_hi:[1,0] neg_lo:[0,1] neg_hi:[0,1]
	v_pk_add_f32 v[36:37], v[36:37], v[174:175] op_sel_hi:[1,0] neg_lo:[0,1] neg_hi:[0,1]
	v_pk_add_f32 v[38:39], v[38:39], v[174:175] op_sel_hi:[1,0] neg_lo:[0,1] neg_hi:[0,1]
	v_pk_add_f32 v[40:41], v[40:41], v[174:175] op_sel_hi:[1,0] neg_lo:[0,1] neg_hi:[0,1]
	v_exp_f32_e32 v34, v34
	v_exp_f32_e32 v35, v35
	v_exp_f32_e32 v36, v36
	v_exp_f32_e32 v37, v37
	v_exp_f32_e32 v38, v38
	v_exp_f32_e32 v39, v39
	v_exp_f32_e32 v40, v40
	v_exp_f32_e32 v41, v41
	v_pk_add_f32 v[238:239], v[34:35], v[36:37]
	v_pk_add_f32 v[238:239], v[238:239], v[38:39]
	v_pk_add_f32 v[238:239], v[238:239], v[40:41]
	v_cvt_pk_bf16_f32 v164, v34, v35
	v_cvt_pk_bf16_f32 v165, v36, v37
	v_cvt_pk_bf16_f32 v166, v38, v39
	v_cvt_pk_bf16_f32 v167, v40, v41
	v_pk_add_f32 v[42:43], v[42:43], v[174:175] op_sel_hi:[1,0] neg_lo:[0,1] neg_hi:[0,1]
	v_pk_add_f32 v[44:45], v[44:45], v[174:175] op_sel_hi:[1,0] neg_lo:[0,1] neg_hi:[0,1]
	v_pk_add_f32 v[46:47], v[46:47], v[174:175] op_sel_hi:[1,0] neg_lo:[0,1] neg_hi:[0,1]
	v_pk_add_f32 v[48:49], v[48:49], v[174:175] op_sel_hi:[1,0] neg_lo:[0,1] neg_hi:[0,1]
	s_waitcnt vmcnt(0)
	v_mfma_f32_32x32x16_bf16 v[2:17], v[130:133], v[164:167], v[2:17]
	v_mfma_f32_32x32x16_bf16 v[18:33], v[146:149], v[164:167], v[18:33]
	v_exp_f32_e32 v42, v42
	v_exp_f32_e32 v43, v43
	v_exp_f32_e32 v44, v44
	v_exp_f32_e32 v45, v45
	v_exp_f32_e32 v46, v46
	v_exp_f32_e32 v47, v47
	v_exp_f32_e32 v48, v48
	v_exp_f32_e32 v49, v49
	v_pk_add_f32 v[238:239], v[238:239], v[42:43]
	v_pk_add_f32 v[238:239], v[238:239], v[44:45]
	v_pk_add_f32 v[238:239], v[238:239], v[46:47]
	v_pk_add_f32 v[238:239], v[238:239], v[48:49]
	v_cvt_pk_bf16_f32 v168, v42, v43
	v_cvt_pk_bf16_f32 v169, v44, v45
	v_cvt_pk_bf16_f32 v170, v46, v47
	v_cvt_pk_bf16_f32 v171, v48, v49
	v_pk_add_f32 v[50:51], v[50:51], v[174:175] op_sel_hi:[1,0] neg_lo:[0,1] neg_hi:[0,1]
	v_pk_add_f32 v[52:53], v[52:53], v[174:175] op_sel_hi:[1,0] neg_lo:[0,1] neg_hi:[0,1]
	v_pk_add_f32 v[54:55], v[54:55], v[174:175] op_sel_hi:[1,0] neg_lo:[0,1] neg_hi:[0,1]
	v_pk_add_f32 v[56:57], v[56:57], v[174:175] op_sel_hi:[1,0] neg_lo:[0,1] neg_hi:[0,1]
	v_mfma_f32_32x32x16_bf16 v[2:17], v[134:137], v[168:171], v[2:17]
	v_mfma_f32_32x32x16_bf16 v[18:33], v[150:153], v[168:171], v[18:33]
	v_exp_f32_e32 v50, v50
	v_exp_f32_e32 v51, v51
	v_exp_f32_e32 v52, v52
	v_exp_f32_e32 v53, v53
	v_exp_f32_e32 v54, v54
	v_exp_f32_e32 v55, v55
	v_exp_f32_e32 v56, v56
	v_exp_f32_e32 v57, v57
	v_pk_add_f32 v[238:239], v[238:239], v[50:51]
	v_pk_add_f32 v[238:239], v[238:239], v[52:53]
	v_pk_add_f32 v[238:239], v[238:239], v[54:55]
	v_pk_add_f32 v[238:239], v[238:239], v[56:57]
	v_cvt_pk_bf16_f32 v164, v50, v51
	v_cvt_pk_bf16_f32 v165, v52, v53
	v_cvt_pk_bf16_f32 v166, v54, v55
	v_cvt_pk_bf16_f32 v167, v56, v57
	v_pk_add_f32 v[58:59], v[58:59], v[174:175] op_sel_hi:[1,0] neg_lo:[0,1] neg_hi:[0,1]
	v_pk_add_f32 v[60:61], v[60:61], v[174:175] op_sel_hi:[1,0] neg_lo:[0,1] neg_hi:[0,1]
	v_pk_add_f32 v[62:63], v[62:63], v[174:175] op_sel_hi:[1,0] neg_lo:[0,1] neg_hi:[0,1]
	v_pk_add_f32 v[64:65], v[64:65], v[174:175] op_sel_hi:[1,0] neg_lo:[0,1] neg_hi:[0,1]
	v_mfma_f32_32x32x16_bf16 v[2:17], v[138:141], v[164:167], v[2:17]
	v_mfma_f32_32x32x16_bf16 v[18:33], v[154:157], v[164:167], v[18:33]
	v_exp_f32_e32 v58, v58
	v_exp_f32_e32 v59, v59
	v_exp_f32_e32 v60, v60
	v_exp_f32_e32 v61, v61
	v_exp_f32_e32 v62, v62
	v_exp_f32_e32 v63, v63
	v_exp_f32_e32 v64, v64
	v_exp_f32_e32 v65, v65
	v_pk_add_f32 v[238:239], v[238:239], v[58:59]
	v_pk_add_f32 v[238:239], v[238:239], v[60:61]
	v_pk_add_f32 v[238:239], v[238:239], v[62:63]
	v_pk_add_f32 v[238:239], v[238:239], v[64:65]
	v_cvt_pk_bf16_f32 v168, v58, v59
	v_cvt_pk_bf16_f32 v169, v60, v61
	v_cvt_pk_bf16_f32 v170, v62, v63
	v_cvt_pk_bf16_f32 v171, v64, v65
	s_nop 1
	v_mfma_f32_32x32x16_bf16 v[2:17], v[142:145], v[168:171], v[2:17]
	v_mfma_f32_32x32x16_bf16 v[18:33], v[158:161], v[168:171], v[18:33]
	v_add_f32_e32 v240, v238, v239
	v_add_f32_e32 v1, v1, v240
.Lfe_done:
	s_nop 7
	s_nop 7
	v_mov_b32_e32 v191, v1
	v_mov_b32_e32 v192, v162
	v_mov_b64_e32 v[146:147], v[2:3]
	v_mov_b64_e32 v[148:149], v[4:5]
	v_mov_b64_e32 v[150:151], v[6:7]
	v_mov_b64_e32 v[152:153], v[8:9]
	v_mov_b64_e32 v[154:155], v[10:11]
	v_mov_b64_e32 v[156:157], v[12:13]
	v_mov_b64_e32 v[158:159], v[14:15]
	v_mov_b64_e32 v[160:161], v[16:17]
	v_mov_b64_e32 v[162:163], v[18:19]
	v_mov_b64_e32 v[164:165], v[20:21]
	v_mov_b64_e32 v[166:167], v[22:23]
	v_mov_b64_e32 v[168:169], v[24:25]
	v_mov_b64_e32 v[170:171], v[26:27]
	v_mov_b64_e32 v[172:173], v[28:29]
	v_mov_b64_e32 v[174:175], v[30:31]
	v_mov_b64_e32 v[176:177], v[32:33]
	s_and_saveexec_b64 s[12:13], s[8:9]
	s_cbranch_execz .LBB0_1399
	v_not_b32_e32 v3, v192
	v_or_b32_e32 v4, 0x80000000, v192
	v_cmp_gt_i32_e32 vcc, 0, v192
	v_add_u32_e32 v2, 0x10400, v183
	s_nop 0
	v_cndmask_b32_e32 v3, v4, v3, vcc
	ds_write_b32 v2, v3

.Lit_exp:
	v_cndmask_b32_e64 v35, v219, v208, s[14:15]
	v_sub_f32_e32 v35, v35, v140
	v_cndmask_b32_e64 v142, 1.0, v222, s[16:17]
	v_cndmask_b32_e64 v144, -v140, v35, s[16:17]
	v_pk_fma_f32 v[18:19], v[18:19], v[142:143], v[144:145] op_sel_hi:[1,0,0]
	v_pk_fma_f32 v[20:21], v[20:21], v[142:143], v[144:145] op_sel_hi:[1,0,0]
	v_pk_fma_f32 v[22:23], v[22:23], v[142:143], v[144:145] op_sel_hi:[1,0,0]
	v_pk_fma_f32 v[24:25], v[24:25], v[142:143], v[144:145] op_sel_hi:[1,0,0]
	v_exp_f32_e32 v18, v18
	v_exp_f32_e32 v19, v19
	v_exp_f32_e32 v20, v20
	v_exp_f32_e32 v21, v21
	v_exp_f32_e32 v22, v22
	v_exp_f32_e32 v23, v23
	v_exp_f32_e32 v24, v24
	v_exp_f32_e32 v25, v25
	v_pk_add_f32 v[132:133], v[18:19], v[20:21]
	v_pk_add_f32 v[132:133], v[132:133], v[22:23]
	v_pk_add_f32 v[132:133], v[132:133], v[24:25]
	v_cvt_pk_bf16_f32 v234, v18, v19
	v_cvt_pk_bf16_f32 v235, v20, v21
	v_cvt_pk_bf16_f32 v236, v22, v23
	v_cvt_pk_bf16_f32 v237, v24, v25
	v_pk_fma_f32 v[242:243], v[26:27], v[142:143], v[144:145] op_sel_hi:[1,0,0]
	v_pk_fma_f32 v[244:245], v[28:29], v[142:143], v[144:145] op_sel_hi:[1,0,0]
	v_pk_fma_f32 v[246:247], v[30:31], v[142:143], v[144:145] op_sel_hi:[1,0,0]
	v_pk_fma_f32 v[248:249], v[32:33], v[142:143], v[144:145] op_sel_hi:[1,0,0]
	v_mfma_f32_32x32x16_bf16 v[18:33], v[74:77], v[234:237], 0
	v_mfma_f32_32x32x16_bf16 v[34:49], v[94:97], v[234:237], 0
	v_exp_f32_e32 v242, v242
	v_exp_f32_e32 v243, v243
	v_exp_f32_e32 v244, v244
	v_exp_f32_e32 v245, v245
	v_exp_f32_e32 v246, v246
	v_exp_f32_e32 v247, v247
	v_exp_f32_e32 v248, v248
	v_exp_f32_e32 v249, v249
	v_pk_add_f32 v[132:133], v[132:133], v[242:243]
	v_pk_add_f32 v[132:133], v[132:133], v[244:245]
	v_pk_add_f32 v[132:133], v[132:133], v[246:247]
	v_pk_add_f32 v[132:133], v[132:133], v[248:249]
	v_cvt_pk_bf16_f32 v238, v242, v243
	v_cvt_pk_bf16_f32 v239, v244, v245
	v_cvt_pk_bf16_f32 v240, v246, v247
	v_cvt_pk_bf16_f32 v241, v248, v249
	v_pk_fma_f32 v[2:3], v[2:3], v[142:143], v[144:145] op_sel_hi:[1,0,0]
	v_pk_fma_f32 v[4:5], v[4:5], v[142:143], v[144:145] op_sel_hi:[1,0,0]
	v_pk_fma_f32 v[6:7], v[6:7], v[142:143], v[144:145] op_sel_hi:[1,0,0]
	v_pk_fma_f32 v[8:9], v[8:9], v[142:143], v[144:145] op_sel_hi:[1,0,0]
	v_mfma_f32_32x32x16_bf16 v[18:33], v[70:73], v[238:241], v[18:33]
	v_mfma_f32_32x32x16_bf16 v[34:49], v[102:105], v[238:241], v[34:49]
	v_exp_f32_e32 v2, v2
	v_exp_f32_e32 v3, v3
	v_exp_f32_e32 v4, v4
	v_exp_f32_e32 v5, v5
	v_exp_f32_e32 v6, v6
	v_exp_f32_e32 v7, v7
	v_exp_f32_e32 v8, v8
	v_exp_f32_e32 v9, v9
	v_pk_add_f32 v[132:133], v[132:133], v[2:3]
	v_pk_add_f32 v[132:133], v[132:133], v[4:5]
	v_pk_add_f32 v[132:133], v[132:133], v[6:7]
	v_pk_add_f32 v[132:133], v[132:133], v[8:9]
	v_cvt_pk_bf16_f32 v234, v2, v3
	v_cvt_pk_bf16_f32 v235, v4, v5
	v_cvt_pk_bf16_f32 v236, v6, v7
	v_cvt_pk_bf16_f32 v237, v8, v9
	v_pk_fma_f32 v[10:11], v[10:11], v[142:143], v[144:145] op_sel_hi:[1,0,0]
	v_pk_fma_f32 v[12:13], v[12:13], v[142:143], v[144:145] op_sel_hi:[1,0,0]
	v_pk_fma_f32 v[14:15], v[14:15], v[142:143], v[144:145] op_sel_hi:[1,0,0]
	v_pk_fma_f32 v[16:17], v[16:17], v[142:143], v[144:145] op_sel_hi:[1,0,0]
	v_mfma_f32_32x32x16_bf16 v[18:33], v[86:89], v[234:237], v[18:33]
	v_mfma_f32_32x32x16_bf16 v[34:49], v[106:109], v[234:237], v[34:49]
	v_exp_f32_e32 v10, v10
	v_exp_f32_e32 v11, v11
	v_exp_f32_e32 v12, v12
	v_exp_f32_e32 v13, v13
	v_exp_f32_e32 v14, v14
	v_exp_f32_e32 v15, v15
	v_exp_f32_e32 v16, v16
	v_exp_f32_e32 v17, v17
	v_pk_add_f32 v[132:133], v[132:133], v[10:11]
	v_pk_add_f32 v[132:133], v[132:133], v[12:13]
	v_pk_add_f32 v[132:133], v[132:133], v[14:15]
	v_pk_add_f32 v[132:133], v[132:133], v[16:17]
	v_cvt_pk_bf16_f32 v238, v10, v11
	v_cvt_pk_bf16_f32 v239, v12, v13
	v_cvt_pk_bf16_f32 v240, v14, v15
	v_cvt_pk_bf16_f32 v241, v16, v17
	s_nop 1
	v_mfma_f32_32x32x16_bf16 v[18:33], v[82:85], v[238:241], v[18:33]
	v_mfma_f32_32x32x16_bf16 v[34:49], v[110:113], v[238:241], v[34:49]
	v_add_f32_e32 v134, v132, v133
	v_mov_b32_e32 v2, v134
	s_nop 1
	v_permlane32_swap_b32_e32 v134, v2
	v_add_f32_e32 v2, v134, v2
	s_and_saveexec_b64 s[16:17], s[60:61]
	s_cbranch_execz .Lit_nols
	v_cvt_i32_f32_e32 v3, v2
	v_add_u32_e32 v4, 0x10800, v190
	ds_add_u32 v4, v3

.Lfe_restore:
	v_mov_b64_e32 v[2:3], v[146:147]
	v_mov_b64_e32 v[4:5], v[148:149]
	v_mov_b64_e32 v[6:7], v[150:151]
	v_mov_b64_e32 v[8:9], v[152:153]
	v_mov_b64_e32 v[10:11], v[154:155]
	v_mov_b64_e32 v[12:13], v[156:157]
	v_mov_b64_e32 v[14:15], v[158:159]
	v_mov_b64_e32 v[16:17], v[160:161]
	v_mov_b64_e32 v[18:19], v[162:163]
	v_mov_b64_e32 v[20:21], v[164:165]
	v_mov_b64_e32 v[22:23], v[166:167]
	v_mov_b64_e32 v[24:25], v[168:169]
	v_mov_b64_e32 v[26:27], v[170:171]
	v_mov_b64_e32 v[28:29], v[172:173]
	v_mov_b64_e32 v[30:31], v[174:175]
	v_mov_b64_e32 v[32:33], v[176:177]
	v_mov_b32_e32 v1, v191
	v_mov_b32_e32 v162, v192
	s_branch .LBB0_1481
